# P1 K-loop: skip MFMA blocks of the all-zero half of the meta-row tile and of the unused waves of the rotary-key tile
# speedup vs baseline: 1.0101x; 1.0101x over previous
;     __device__ bool next(int i, Unit& u) const { if (!so.next(i >> 1, u)) return false; u.sel = i & 1; return true; }
;     __host__ __device__ bool next(int i, Unit& u) const {
;         const long L = (long)i * G + c; if (L >= nwg) return false;
;         int wgid = (int)L; { const int q = nwg / NXCD, r = nwg % NXCD, xcd = wgid % NXCD, off = wgid / NXCD; wgid = (xcd < r ? xcd * (q + 1) : r * (q + 1) + (xcd - r) * q) + off; }
;         const int nig = WGM * nN, gid = wgid / nig, fm = gid * WGM, gsz = (nM - fm) < WGM ? (nM - fm) : WGM;
;         u.pm = fm + ((wgid % nig) % gsz); u.pn = (wgid % nig) / gsz; u.sel = 0; return true;
; template <class Epi, class Sched, bool ALIGN_EPI = false, bool SP2 = false>
; __device__ __forceinline__ void gemm_phase(PG8_LAS unsigned char* lds, const Gemm g, const Sched& S, const Epi& E) {
;     int tid_ = threadIdx.x; asm volatile("" : "+v"(tid_));
;     const int tid = tid_, wid = __builtin_amdgcn_readfirstlane(tid >> 6), lane = tid & 63, wr = wid >> 2, wc = wid & 3, fr = lane & 15, fq = lane >> 4;
.LBB0_192:
	s_or_b64 exec, exec, s[0:1]
	v_readfirstlane_b32 s99, v201
	s_nop 3
	s_bfe_u32 s99, s99, 0x20006
	s_cmp_lg_u32 s99, 0
	s_cselect_b32 s99, 3, 0
	v_mov_b32_e32 v1, v201
	s_cmpk_lt_i32 s2, 0x1b1b
	s_waitcnt lgkmcnt(0)
	s_barrier
	s_movk_i32 s0, 0x400
	v_readfirstlane_b32 s3, v1
	s_cselect_b64 s[4:5], -1, 0
	s_cmpk_gt_i32 s2, 0x1b1a
	s_cbranch_scc1 .LBB0_198
	s_ashr_i32 s1, s2, 31
	s_lshr_b32 s1, s1, 29
	s_add_i32 s1, s2, s1
	s_and_b32 s6, s1, -8
	s_sub_i32 s8, s2, s6
	s_cmp_gt_i32 s8, 2
	s_cbranch_scc0 .LBB0_195
	s_mul_i32 s6, s8, 0x363
	s_add_i32 s9, s6, 3
	s_cbranch_execz .LBB0_196
	s_branch .LBB0_197

; #define PG8_STAGE(bufoff, gbase, voff) do { _Pragma("unroll") for (int _i = 0; _i < 2; ++_i) \
;         __builtin_amdgcn_global_load_lds((const unsigned*)((const char*)(gbase) + (voff)[_i]), (PG8_LAS unsigned*)(lds + (bufoff) + ldsw + _i * 8192), 16, 0, 0); } while (0)
; #define PG8_LDA(dst, b, h) do { _Pragma("unroll") for (int m = 0; m < 4; ++m) _Pragma("unroll") for (int k = 0; k < 2; ++k) dst[m][k] = *(const PG8_LAS bf16x8*)(lds + PG8_SA(b, h) + aoff + m * 2048 + k * 1024); } while (0)
; #define PG8_LDB(dst, b, h) do { _Pragma("unroll") for (int n = 0; n < 2; ++n) _Pragma("unroll") for (int k = 0; k < 2; ++k) dst[n][k] = *(const PG8_LAS bf16x8*)(lds + PG8_SB(b, h) + boff + n * 2048 + k * 1024); } while (0)
; #define PG8_MMA(ai, bj, At, Bt) do { __builtin_amdgcn_s_setprio(1); _Pragma("unroll") for (int m = 0; m < 4; ++m) _Pragma("unroll") for (int n = 0; n < 2; ++n) _Pragma("unroll") for (int k = 0; k < 2; ++k) \
;         acc[ai][bj][m][n] = __builtin_amdgcn_mfma_f32_16x16x32_bf16(Bt[n][k], At[m][k], acc[ai][bj][m][n], 0, 0, 0); __builtin_amdgcn_s_setprio(0); } while (0)
; #define PG8_WAIT_V(n) asm volatile("s_waitcnt vmcnt(" #n ")" ::: "memory")
; template <class Epi, class Sched, bool ALIGN_EPI = false, bool SP2 = false>
; __device__ __forceinline__ void gemm_phase(PG8_LAS unsigned char* lds, const Gemm g, const Sched& S, const Epi& E) {
;     ...
;     f32x4 acc[2][2][4][2];
; #pragma unroll
;     for (int a = 0; a < 2; ++a)
; #pragma unroll
;         for (int b = 0; b < 2; ++b)
; #pragma unroll
;             for (int m = 0; m < 4; ++m)
; #pragma unroll
;                 for (int n = 0; n < 2; ++n) acc[a][b][m][n] = (f32x4){0.f, 0.f, 0.f, 0.f};
;     ...
;         for (int t = 0; t < nt; t += 2) {
;             const bool last = (t == nt - 2);
;             const char* a1 = cA + (size_t)(t + 1) * kstep;
;             const char* a2 = last ? nA : cA + (size_t)(t + 2) * kstep; const char* b2 = last ? nB : cB + (size_t)(t + 2) * kstep;
;             const char* a3 = a2 + kstep; const char* b3 = b2 + kstep;
;             if (last && has_next) S.a_ready(nxt);
;             if constexpr (SP2) {
;             PG8_LDB(B0, 0, 0); PG8_LDB(B1, 0, 1); PG8_SCHED; PG8_LDA(At, 0, 0); PG8_STAGE(PG8_SA(1, 1), a1 + hstep, voffA);
;             PG8_WAIT_V(8); PG8_WAIT_L(0); PG8_BAR; PG8_MMA(0, 0, At, B0); PG8_MMA(0, 1, At, B1); PG8_BAR; PG8_SCHED;
.LBB0_214:
	v_mov_b32_e32 v2, v0
	v_mov_b32_e32 v3, v0
	v_mov_b32_e32 v1, v0
	v_mov_b64_e32 v[128:129], v[2:3]
	v_mov_b64_e32 v[124:125], v[2:3]
	v_mov_b64_e32 v[112:113], v[2:3]
	v_mov_b64_e32 v[108:109], v[2:3]
	v_mov_b64_e32 v[96:97], v[2:3]
	v_mov_b64_e32 v[92:93], v[2:3]
	v_mov_b64_e32 v[80:81], v[2:3]
	v_mov_b64_e32 v[76:77], v[2:3]
	v_mov_b64_e32 v[120:121], v[2:3]
	v_mov_b64_e32 v[116:117], v[2:3]
	v_mov_b64_e32 v[104:105], v[2:3]
	v_mov_b64_e32 v[100:101], v[2:3]
	v_mov_b64_e32 v[88:89], v[2:3]
	v_mov_b64_e32 v[84:85], v[2:3]
	v_mov_b64_e32 v[72:73], v[2:3]
	v_mov_b64_e32 v[68:69], v[2:3]
	v_mov_b64_e32 v[64:65], v[2:3]
	v_mov_b64_e32 v[60:61], v[2:3]
	v_mov_b64_e32 v[48:49], v[2:3]
	v_mov_b64_e32 v[44:45], v[2:3]
	v_mov_b64_e32 v[32:33], v[2:3]
	v_mov_b64_e32 v[28:29], v[2:3]
	v_mov_b64_e32 v[16:17], v[2:3]
	v_mov_b64_e32 v[12:13], v[2:3]
	v_mov_b64_e32 v[56:57], v[2:3]
	v_mov_b64_e32 v[52:53], v[2:3]
	v_mov_b64_e32 v[40:41], v[2:3]
	v_mov_b64_e32 v[36:37], v[2:3]
	v_mov_b64_e32 v[24:25], v[2:3]
	v_mov_b64_e32 v[20:21], v[2:3]
	v_mov_b64_e32 v[8:9], v[2:3]
	v_mov_b64_e32 v[126:127], v[0:1]
	v_mov_b64_e32 v[122:123], v[0:1]
	v_mov_b64_e32 v[110:111], v[0:1]
	v_mov_b64_e32 v[106:107], v[0:1]
	v_mov_b64_e32 v[94:95], v[0:1]
	v_mov_b64_e32 v[90:91], v[0:1]
	v_mov_b64_e32 v[78:79], v[0:1]
	v_mov_b64_e32 v[74:75], v[0:1]
	v_mov_b64_e32 v[118:119], v[0:1]
	v_mov_b64_e32 v[114:115], v[0:1]
	v_mov_b64_e32 v[102:103], v[0:1]
	v_mov_b64_e32 v[98:99], v[0:1]
	v_mov_b64_e32 v[86:87], v[0:1]
	v_mov_b64_e32 v[82:83], v[0:1]
	v_mov_b64_e32 v[70:71], v[0:1]
	v_mov_b64_e32 v[66:67], v[0:1]
	v_mov_b64_e32 v[62:63], v[0:1]
	v_mov_b64_e32 v[58:59], v[0:1]
	v_mov_b64_e32 v[46:47], v[0:1]
	v_mov_b64_e32 v[42:43], v[0:1]
	v_mov_b64_e32 v[30:31], v[0:1]
	v_mov_b64_e32 v[26:27], v[0:1]
	v_mov_b64_e32 v[14:15], v[0:1]
	v_mov_b64_e32 v[10:11], v[0:1]
	v_mov_b64_e32 v[54:55], v[0:1]
	v_mov_b64_e32 v[50:51], v[0:1]
	v_mov_b64_e32 v[38:39], v[0:1]
	v_mov_b64_e32 v[34:35], v[0:1]
	v_mov_b64_e32 v[22:23], v[0:1]
	v_mov_b64_e32 v[18:19], v[0:1]
	v_mov_b64_e32 v[6:7], v[0:1]
	v_mov_b64_e32 v[4:5], v[2:3]
	s_andn2_b64 vcc, exec, s[56:57]
	v_mov_b64_e32 v[2:3], v[0:1]
	s_cbranch_vccnz .LBB0_217
	s_cmp_eq_u32 s48, 0x100
	s_cselect_b32 s100, 1, 0
	s_cmp_eq_u32 s49, 26
	s_cselect_b32 s101, s99, 0
	s_or_b32 s100, s100, s101
	s_add_u32 s0, s72, 0x80
	s_addc_u32 s1, s73, 0
	s_add_u32 s61, s6, 0x100
	s_addc_u32 s72, s7, 0
	s_mov_b32 s6, 0
.LBB0_216:
	ds_read_b128 v[130:133], v178
	ds_read_b128 v[134:137], v178 offset:1024
	ds_read_b128 v[138:141], v178 offset:2048
	ds_read_b128 v[142:145], v178 offset:3072
	ds_read_b128 v[168:171], v179
	ds_read_b128 v[172:175], v179 offset:1024
	ds_read_b128 v[182:185], v179 offset:2048
	ds_read_b128 v[186:189], v179 offset:3072
	s_add_i32 s73, s6, 2
	s_add_u32 vcc_lo, s0, 0x80
	s_addc_u32 s7, s1, 0
	s_cmp_eq_u32 s92, s6
	s_cselect_b32 s6, s62, vcc_lo
	s_cselect_b32 s7, s63, s7
	s_cselect_b32 vcc_hi, s71, s72
	s_cselect_b32 vcc_lo, s70, s61
	v_lshl_add_u64 v[198:199], s[0:1], 0, v[160:161]
	s_add_i32 m0, s77, 0xc000
	ds_read_b128 v[190:193], v180
	ds_read_b128 v[194:197], v180 offset:1024
	ds_read_b128 v[202:205], v180 offset:2048
	ds_read_b128 v[206:209], v180 offset:3072
	ds_read_b128 v[210:213], v180 offset:4096
	ds_read_b128 v[214:217], v180 offset:5120
	ds_read_b128 v[218:221], v180 offset:6144
	ds_read_b128 v[222:225], v180 offset:7168
	global_load_lds_dwordx4 v[198:199], off
	v_lshl_add_u64 v[198:199], s[0:1], 0, v[162:163]
	s_add_i32 m0, s77, 0xe000
	s_nop 0
	global_load_lds_dwordx4 v[198:199], off
	s_waitcnt vmcnt(8)
	s_waitcnt lgkmcnt(0)
	s_barrier
	s_setprio 1
	s_waitcnt lgkmcnt(0)
	s_bitcmp1_b32 s100, 1
	s_cbranch_scc1 .Lp1skip_0
	v_mfma_f32_16x16x32_bf16 v[126:129], v[130:133], v[190:193], v[126:129]
	v_mfma_f32_16x16x32_bf16 v[122:125], v[138:141], v[190:193], v[122:125]
	v_mfma_f32_16x16x32_bf16 v[110:113], v[130:133], v[202:205], v[110:113]
	v_mfma_f32_16x16x32_bf16 v[106:109], v[138:141], v[202:205], v[106:109]
	v_mfma_f32_16x16x32_bf16 v[94:97], v[130:133], v[210:213], v[94:97]
	v_mfma_f32_16x16x32_bf16 v[90:93], v[138:141], v[210:213], v[90:93]
	v_mfma_f32_16x16x32_bf16 v[78:81], v[130:133], v[218:221], v[78:81]
	v_mfma_f32_16x16x32_bf16 v[74:77], v[138:141], v[218:221], v[74:77]
	v_mfma_f32_16x16x32_bf16 v[126:129], v[134:137], v[194:197], v[126:129]
	v_mfma_f32_16x16x32_bf16 v[122:125], v[142:145], v[194:197], v[122:125]
	v_mfma_f32_16x16x32_bf16 v[110:113], v[134:137], v[206:209], v[110:113]
	v_mfma_f32_16x16x32_bf16 v[106:109], v[142:145], v[206:209], v[106:109]
	v_mfma_f32_16x16x32_bf16 v[94:97], v[134:137], v[214:217], v[94:97]
	v_mfma_f32_16x16x32_bf16 v[90:93], v[142:145], v[214:217], v[90:93]
	v_mfma_f32_16x16x32_bf16 v[78:81], v[134:137], v[222:225], v[78:81]
	v_mfma_f32_16x16x32_bf16 v[74:77], v[142:145], v[222:225], v[74:77]
	s_setprio 0
	s_setprio 1
	v_mfma_f32_16x16x32_bf16 v[118:121], v[168:171], v[190:193], v[118:121]
	v_mfma_f32_16x16x32_bf16 v[114:117], v[182:185], v[190:193], v[114:117]
	v_mfma_f32_16x16x32_bf16 v[102:105], v[168:171], v[202:205], v[102:105]
	v_mfma_f32_16x16x32_bf16 v[98:101], v[182:185], v[202:205], v[98:101]
	v_mfma_f32_16x16x32_bf16 v[86:89], v[168:171], v[210:213], v[86:89]
	v_mfma_f32_16x16x32_bf16 v[82:85], v[182:185], v[210:213], v[82:85]
	v_mfma_f32_16x16x32_bf16 v[70:73], v[168:171], v[218:221], v[70:73]
	v_mfma_f32_16x16x32_bf16 v[66:69], v[182:185], v[218:221], v[66:69]
	v_mfma_f32_16x16x32_bf16 v[118:121], v[172:175], v[194:197], v[118:121]
	v_mfma_f32_16x16x32_bf16 v[114:117], v[186:189], v[194:197], v[114:117]
	v_mfma_f32_16x16x32_bf16 v[102:105], v[172:175], v[206:209], v[102:105]
	v_mfma_f32_16x16x32_bf16 v[98:101], v[186:189], v[206:209], v[98:101]
	v_mfma_f32_16x16x32_bf16 v[86:89], v[172:175], v[214:217], v[86:89]
	v_mfma_f32_16x16x32_bf16 v[82:85], v[186:189], v[214:217], v[82:85]
	v_mfma_f32_16x16x32_bf16 v[70:73], v[172:175], v[222:225], v[70:73]
	v_mfma_f32_16x16x32_bf16 v[66:69], v[186:189], v[222:225], v[66:69]
; #define PG8_STAGE(bufoff, gbase, voff) do { _Pragma("unroll") for (int _i = 0; _i < 2; ++_i) \
;         __builtin_amdgcn_global_load_lds((const unsigned*)((const char*)(gbase) + (voff)[_i]), (PG8_LAS unsigned*)(lds + (bufoff) + ldsw + _i * 8192), 16, 0, 0); } while (0)
; #define PG8_LDA(dst, b, h) do { _Pragma("unroll") for (int m = 0; m < 4; ++m) _Pragma("unroll") for (int k = 0; k < 2; ++k) dst[m][k] = *(const PG8_LAS bf16x8*)(lds + PG8_SA(b, h) + aoff + m * 2048 + k * 1024); } while (0)
; #define PG8_LDB(dst, b, h) do { _Pragma("unroll") for (int n = 0; n < 2; ++n) _Pragma("unroll") for (int k = 0; k < 2; ++k) dst[n][k] = *(const PG8_LAS bf16x8*)(lds + PG8_SB(b, h) + boff + n * 2048 + k * 1024); } while (0)
; #define PG8_MMA(ai, bj, At, Bt) do { __builtin_amdgcn_s_setprio(1); _Pragma("unroll") for (int m = 0; m < 4; ++m) _Pragma("unroll") for (int n = 0; n < 2; ++n) _Pragma("unroll") for (int k = 0; k < 2; ++k) \
;         acc[ai][bj][m][n] = __builtin_amdgcn_mfma_f32_16x16x32_bf16(Bt[n][k], At[m][k], acc[ai][bj][m][n], 0, 0, 0); __builtin_amdgcn_s_setprio(0); } while (0)
; #define PG8_WAIT_V(n) asm volatile("s_waitcnt vmcnt(" #n ")" ::: "memory")
; #define PG8_WAIT_L(n) asm volatile("s_waitcnt lgkmcnt(" #n ")" ::: "memory")
; #define PG8_BAR __builtin_amdgcn_s_barrier()
; #define PG8_SCHED __builtin_amdgcn_sched_barrier(0)
; template <class Epi, class Sched, bool ALIGN_EPI = false, bool SP2 = false>
; __device__ __forceinline__ void gemm_phase(PG8_LAS unsigned char* lds, const Gemm g, const Sched& S, const Epi& E) {
;     ...
;             PG8_WAIT_V(8); PG8_WAIT_L(0); PG8_BAR; PG8_MMA(0, 0, At, B0); PG8_MMA(0, 1, At, B1); PG8_BAR; PG8_SCHED;
;             PG8_LDA(At, 0, 1); PG8_STAGE(PG8_SB(0, 0), b2, voffB); PG8_STAGE(PG8_SB(0, 1), b2 + hstep, voffB); PG8_STAGE(PG8_SA(0, 0), a2, voffA);
;             PG8_WAIT_V(8); PG8_WAIT_L(0); PG8_BAR; PG8_MMA(1, 0, At, B0); PG8_MMA(1, 1, At, B1); PG8_BAR; PG8_SCHED;
;             PG8_LDB(B0, 1, 0); PG8_LDB(B1, 1, 1); PG8_SCHED; PG8_LDA(At, 1, 0); PG8_STAGE(PG8_SA(0, 1), a2 + hstep, voffA);
;             PG8_WAIT_V(8); PG8_WAIT_L(0); PG8_BAR; PG8_MMA(0, 0, At, B0); PG8_MMA(0, 1, At, B1); PG8_BAR; PG8_SCHED;
.Lp1skip_0:
	s_setprio 0
	s_barrier
	s_add_i32 s16, s96, s76
	v_lshl_add_u64 v[198:199], vcc, 0, v[148:149]
	s_mov_b32 m0, s16
	ds_read_b128 v[190:193], v180 offset:16384
	ds_read_b128 v[194:197], v180 offset:17408
	ds_read_b128 v[202:205], v180 offset:18432
	ds_read_b128 v[206:209], v180 offset:19456
	ds_read_b128 v[210:213], v180 offset:20480
	ds_read_b128 v[214:217], v180 offset:21504
	ds_read_b128 v[218:221], v180 offset:22528
	ds_read_b128 v[222:225], v180 offset:23552
	global_load_lds_dwordx4 v[198:199], off
	s_add_i32 m0, s16, 0x2000
	v_lshl_add_u64 v[226:227], vcc, 0, v[152:153]
	s_add_u32 vcc_lo, vcc_lo, s10
	s_addc_u32 vcc_hi, vcc_hi, s11
	s_add_i32 s16, s97, s76
	global_load_lds_dwordx4 v[226:227], off
	v_lshl_add_u64 v[228:229], vcc, 0, v[148:149]
	s_mov_b32 m0, s16
	v_lshl_add_u64 v[230:231], vcc, 0, v[152:153]
	global_load_lds_dwordx4 v[228:229], off
	s_add_i32 m0, s16, 0x2000
	v_lshl_add_u64 v[232:233], s[6:7], 0, v[146:147]
	global_load_lds_dwordx4 v[230:231], off
	s_mov_b32 m0, s77
	v_lshl_add_u64 v[236:237], s[6:7], 0, v[150:151]
	global_load_lds_dwordx4 v[232:233], off
	s_mov_b32 m0, s78
	s_nop 0
	global_load_lds_dwordx4 v[236:237], off
	s_waitcnt vmcnt(8)
	s_waitcnt lgkmcnt(0)
	s_barrier
	s_setprio 1
	s_waitcnt lgkmcnt(0)
	s_bitcmp1_b32 s100, 0
	s_cbranch_scc1 .Lp1skip_1
	v_mfma_f32_16x16x32_bf16 v[62:65], v[130:133], v[190:193], v[62:65]
	v_mfma_f32_16x16x32_bf16 v[58:61], v[138:141], v[190:193], v[58:61]
	v_mfma_f32_16x16x32_bf16 v[46:49], v[130:133], v[202:205], v[46:49]
	v_mfma_f32_16x16x32_bf16 v[42:45], v[138:141], v[202:205], v[42:45]
	v_mfma_f32_16x16x32_bf16 v[30:33], v[130:133], v[210:213], v[30:33]
	v_mfma_f32_16x16x32_bf16 v[26:29], v[138:141], v[210:213], v[26:29]
	v_mfma_f32_16x16x32_bf16 v[14:17], v[130:133], v[218:221], v[14:17]
	v_mfma_f32_16x16x32_bf16 v[10:13], v[138:141], v[218:221], v[10:13]
	v_mfma_f32_16x16x32_bf16 v[62:65], v[134:137], v[194:197], v[62:65]
	v_mfma_f32_16x16x32_bf16 v[58:61], v[142:145], v[194:197], v[58:61]
	v_mfma_f32_16x16x32_bf16 v[46:49], v[134:137], v[206:209], v[46:49]
	v_mfma_f32_16x16x32_bf16 v[42:45], v[142:145], v[206:209], v[42:45]
	v_mfma_f32_16x16x32_bf16 v[30:33], v[134:137], v[214:217], v[30:33]
	v_mfma_f32_16x16x32_bf16 v[26:29], v[142:145], v[214:217], v[26:29]
	v_mfma_f32_16x16x32_bf16 v[14:17], v[134:137], v[222:225], v[14:17]
	v_mfma_f32_16x16x32_bf16 v[10:13], v[142:145], v[222:225], v[10:13]
	s_setprio 0
	s_setprio 1
	v_mfma_f32_16x16x32_bf16 v[54:57], v[168:171], v[190:193], v[54:57]
	v_mfma_f32_16x16x32_bf16 v[50:53], v[182:185], v[190:193], v[50:53]
	v_mfma_f32_16x16x32_bf16 v[38:41], v[168:171], v[202:205], v[38:41]
	v_mfma_f32_16x16x32_bf16 v[34:37], v[182:185], v[202:205], v[34:37]
	v_mfma_f32_16x16x32_bf16 v[22:25], v[168:171], v[210:213], v[22:25]
	v_mfma_f32_16x16x32_bf16 v[18:21], v[182:185], v[210:213], v[18:21]
	v_mfma_f32_16x16x32_bf16 v[6:9], v[168:171], v[218:221], v[6:9]
	v_mfma_f32_16x16x32_bf16 v[2:5], v[182:185], v[218:221], v[2:5]
	v_mfma_f32_16x16x32_bf16 v[54:57], v[172:175], v[194:197], v[54:57]
	v_mfma_f32_16x16x32_bf16 v[50:53], v[186:189], v[194:197], v[50:53]
	v_mfma_f32_16x16x32_bf16 v[38:41], v[172:175], v[206:209], v[38:41]
	v_mfma_f32_16x16x32_bf16 v[34:37], v[186:189], v[206:209], v[34:37]
	v_mfma_f32_16x16x32_bf16 v[22:25], v[172:175], v[214:217], v[22:25]
	v_mfma_f32_16x16x32_bf16 v[18:21], v[186:189], v[214:217], v[18:21]
	v_mfma_f32_16x16x32_bf16 v[6:9], v[172:175], v[222:225], v[6:9]
	v_mfma_f32_16x16x32_bf16 v[2:5], v[186:189], v[222:225], v[2:5]
.Lp1skip_1:
	s_setprio 0
	s_barrier
	s_add_i32 s16, 0, 0x18000
	v_add_u32_e32 v1, s16, v176
	s_add_i32 s17, 0, 0x1c000
	ds_read_b128 v[130:133], v1
	ds_read_b128 v[134:137], v1 offset:1024
	ds_read_b128 v[138:141], v1 offset:2048
	ds_read_b128 v[142:145], v1 offset:3072
	v_add_u32_e32 v1, s17, v176
	ds_read_b128 v[168:171], v1
	ds_read_b128 v[172:175], v1 offset:1024
	ds_read_b128 v[182:185], v1 offset:2048
	ds_read_b128 v[186:189], v1 offset:3072
	s_add_u32 s6, s6, s10
	s_addc_u32 s7, s7, s11
	s_mov_b32 m0, s79
	v_lshl_add_u64 v[238:239], s[6:7], 0, v[146:147]
	ds_read_b128 v[190:193], v180 offset:32768
	ds_read_b128 v[194:197], v180 offset:33792
	ds_read_b128 v[202:205], v180 offset:34816
	ds_read_b128 v[206:209], v180 offset:35840
	ds_read_b128 v[210:213], v180 offset:36864
	ds_read_b128 v[214:217], v180 offset:37888
	ds_read_b128 v[218:221], v180 offset:38912
	ds_read_b128 v[222:225], v180 offset:39936
	global_load_lds_dwordx4 v[238:239], off
	v_lshl_add_u64 v[238:239], s[6:7], 0, v[150:151]
	s_mov_b32 m0, s80
	s_nop 0
	global_load_lds_dwordx4 v[238:239], off
	s_waitcnt vmcnt(8)
	s_waitcnt lgkmcnt(0)
	s_barrier
	s_setprio 1
	s_waitcnt lgkmcnt(0)
	s_bitcmp1_b32 s100, 1
	s_cbranch_scc1 .Lp1skip_2
	v_mfma_f32_16x16x32_bf16 v[126:129], v[130:133], v[190:193], v[126:129]
	v_mfma_f32_16x16x32_bf16 v[122:125], v[138:141], v[190:193], v[122:125]
	v_mfma_f32_16x16x32_bf16 v[110:113], v[130:133], v[202:205], v[110:113]
	v_mfma_f32_16x16x32_bf16 v[106:109], v[138:141], v[202:205], v[106:109]
	v_mfma_f32_16x16x32_bf16 v[94:97], v[130:133], v[210:213], v[94:97]
	v_mfma_f32_16x16x32_bf16 v[90:93], v[138:141], v[210:213], v[90:93]
	v_mfma_f32_16x16x32_bf16 v[78:81], v[130:133], v[218:221], v[78:81]
	v_mfma_f32_16x16x32_bf16 v[74:77], v[138:141], v[218:221], v[74:77]
	v_mfma_f32_16x16x32_bf16 v[126:129], v[134:137], v[194:197], v[126:129]
	v_mfma_f32_16x16x32_bf16 v[122:125], v[142:145], v[194:197], v[122:125]
	v_mfma_f32_16x16x32_bf16 v[110:113], v[134:137], v[206:209], v[110:113]
	v_mfma_f32_16x16x32_bf16 v[106:109], v[142:145], v[206:209], v[106:109]
	v_mfma_f32_16x16x32_bf16 v[94:97], v[134:137], v[214:217], v[94:97]
	v_mfma_f32_16x16x32_bf16 v[90:93], v[142:145], v[214:217], v[90:93]
	v_mfma_f32_16x16x32_bf16 v[78:81], v[134:137], v[222:225], v[78:81]
	v_mfma_f32_16x16x32_bf16 v[74:77], v[142:145], v[222:225], v[74:77]
	s_setprio 0
	s_setprio 1
	v_mfma_f32_16x16x32_bf16 v[118:121], v[168:171], v[190:193], v[118:121]
	v_mfma_f32_16x16x32_bf16 v[114:117], v[182:185], v[190:193], v[114:117]
	v_mfma_f32_16x16x32_bf16 v[102:105], v[168:171], v[202:205], v[102:105]
	v_mfma_f32_16x16x32_bf16 v[98:101], v[182:185], v[202:205], v[98:101]
	v_mfma_f32_16x16x32_bf16 v[86:89], v[168:171], v[210:213], v[86:89]
	v_mfma_f32_16x16x32_bf16 v[82:85], v[182:185], v[210:213], v[82:85]
	v_mfma_f32_16x16x32_bf16 v[70:73], v[168:171], v[218:221], v[70:73]
	v_mfma_f32_16x16x32_bf16 v[66:69], v[182:185], v[218:221], v[66:69]
	v_mfma_f32_16x16x32_bf16 v[118:121], v[172:175], v[194:197], v[118:121]
	v_mfma_f32_16x16x32_bf16 v[114:117], v[186:189], v[194:197], v[114:117]
	v_mfma_f32_16x16x32_bf16 v[102:105], v[172:175], v[206:209], v[102:105]
	v_mfma_f32_16x16x32_bf16 v[98:101], v[186:189], v[206:209], v[98:101]
	v_mfma_f32_16x16x32_bf16 v[86:89], v[172:175], v[214:217], v[86:89]
	v_mfma_f32_16x16x32_bf16 v[82:85], v[186:189], v[214:217], v[82:85]
	v_mfma_f32_16x16x32_bf16 v[70:73], v[172:175], v[222:225], v[70:73]
	v_mfma_f32_16x16x32_bf16 v[66:69], v[186:189], v[222:225], v[66:69]
; #define PG8_STAGE(bufoff, gbase, voff) do { _Pragma("unroll") for (int _i = 0; _i < 2; ++_i) \
;         __builtin_amdgcn_global_load_lds((const unsigned*)((const char*)(gbase) + (voff)[_i]), (PG8_LAS unsigned*)(lds + (bufoff) + ldsw + _i * 8192), 16, 0, 0); } while (0)
; #define PG8_LDA(dst, b, h) do { _Pragma("unroll") for (int m = 0; m < 4; ++m) _Pragma("unroll") for (int k = 0; k < 2; ++k) dst[m][k] = *(const PG8_LAS bf16x8*)(lds + PG8_SA(b, h) + aoff + m * 2048 + k * 1024); } while (0)
; #define PG8_MMA(ai, bj, At, Bt) do { __builtin_amdgcn_s_setprio(1); _Pragma("unroll") for (int m = 0; m < 4; ++m) _Pragma("unroll") for (int n = 0; n < 2; ++n) _Pragma("unroll") for (int k = 0; k < 2; ++k) \
;         acc[ai][bj][m][n] = __builtin_amdgcn_mfma_f32_16x16x32_bf16(Bt[n][k], At[m][k], acc[ai][bj][m][n], 0, 0, 0); __builtin_amdgcn_s_setprio(0); } while (0)
; #define PG8_WAIT_V(n) asm volatile("s_waitcnt vmcnt(" #n ")" ::: "memory")
; #define PG8_WAIT_L(n) asm volatile("s_waitcnt lgkmcnt(" #n ")" ::: "memory")
; #define PG8_BAR __builtin_amdgcn_s_barrier()
; #define PG8_SCHED __builtin_amdgcn_sched_barrier(0)
; template <class Epi, class Sched, bool ALIGN_EPI = false, bool SP2 = false>
; __device__ __forceinline__ void gemm_phase(PG8_LAS unsigned char* lds, const Gemm g, const Sched& S, const Epi& E) {
;     ...
;             PG8_LDA(At, 1, 1); PG8_STAGE(PG8_SB(1, 0), b3, voffB); PG8_STAGE(PG8_SB(1, 1), b3 + hstep, voffB); PG8_STAGE(PG8_SA(1, 0), a3, voffA);
;             PG8_WAIT_V(8); PG8_WAIT_L(0); PG8_BAR; PG8_MMA(1, 0, At, B0); PG8_MMA(1, 1, At, B1); PG8_BAR; PG8_SCHED;
.Lp1skip_2:
	s_setprio 0
	s_barrier
	s_add_i32 s6, s16, s76
	v_lshl_add_u64 v[198:199], v[198:199], 0, s[54:55]
	s_mov_b32 m0, s6
	ds_read_b128 v[190:193], v180 offset:49152
	ds_read_b128 v[194:197], v180 offset:50176
	ds_read_b128 v[202:205], v180 offset:51200
	ds_read_b128 v[206:209], v180 offset:52224
	ds_read_b128 v[210:213], v180 offset:53248
	ds_read_b128 v[214:217], v180 offset:54272
	ds_read_b128 v[218:221], v180 offset:55296
	ds_read_b128 v[222:225], v180 offset:56320
	global_load_lds_dwordx4 v[198:199], off
	v_lshl_add_u64 v[198:199], v[226:227], 0, s[54:55]
	s_add_i32 m0, s6, 0x2000
	s_add_i32 s6, s17, s76
	global_load_lds_dwordx4 v[198:199], off
	v_lshl_add_u64 v[198:199], v[228:229], 0, s[54:55]
	s_mov_b32 m0, s6
	s_nop 0
	global_load_lds_dwordx4 v[198:199], off
	v_lshl_add_u64 v[198:199], v[230:231], 0, s[54:55]
	s_add_i32 m0, s6, 0x2000
	s_nop 0
	global_load_lds_dwordx4 v[198:199], off
	v_lshl_add_u64 v[198:199], v[232:233], 0, s[54:55]
	s_mov_b32 m0, s82
	s_nop 0
	global_load_lds_dwordx4 v[198:199], off
	v_lshl_add_u64 v[198:199], v[236:237], 0, s[54:55]
	s_mov_b32 m0, s83
	s_nop 0
	global_load_lds_dwordx4 v[198:199], off
	s_waitcnt vmcnt(8)
	s_waitcnt lgkmcnt(0)
	s_barrier
	s_setprio 1
	s_waitcnt lgkmcnt(0)
	s_bitcmp1_b32 s100, 0
	s_cbranch_scc1 .Lp1skip_3
	v_mfma_f32_16x16x32_bf16 v[62:65], v[130:133], v[190:193], v[62:65]
	v_mfma_f32_16x16x32_bf16 v[58:61], v[138:141], v[190:193], v[58:61]
	v_mfma_f32_16x16x32_bf16 v[46:49], v[130:133], v[202:205], v[46:49]
	v_mfma_f32_16x16x32_bf16 v[42:45], v[138:141], v[202:205], v[42:45]
	v_mfma_f32_16x16x32_bf16 v[30:33], v[130:133], v[210:213], v[30:33]
	v_mfma_f32_16x16x32_bf16 v[26:29], v[138:141], v[210:213], v[26:29]
	v_mfma_f32_16x16x32_bf16 v[14:17], v[130:133], v[218:221], v[14:17]
	v_mfma_f32_16x16x32_bf16 v[10:13], v[138:141], v[218:221], v[10:13]
	v_mfma_f32_16x16x32_bf16 v[62:65], v[134:137], v[194:197], v[62:65]
	v_mfma_f32_16x16x32_bf16 v[58:61], v[142:145], v[194:197], v[58:61]
	v_mfma_f32_16x16x32_bf16 v[46:49], v[134:137], v[206:209], v[46:49]
	v_mfma_f32_16x16x32_bf16 v[42:45], v[142:145], v[206:209], v[42:45]
	v_mfma_f32_16x16x32_bf16 v[30:33], v[134:137], v[214:217], v[30:33]
	v_mfma_f32_16x16x32_bf16 v[26:29], v[142:145], v[214:217], v[26:29]
	v_mfma_f32_16x16x32_bf16 v[14:17], v[134:137], v[222:225], v[14:17]
	v_mfma_f32_16x16x32_bf16 v[10:13], v[142:145], v[222:225], v[10:13]
	s_setprio 0
	s_setprio 1
	v_mfma_f32_16x16x32_bf16 v[54:57], v[168:171], v[190:193], v[54:57]
	v_mfma_f32_16x16x32_bf16 v[50:53], v[182:185], v[190:193], v[50:53]
	v_mfma_f32_16x16x32_bf16 v[38:41], v[168:171], v[202:205], v[38:41]
	v_mfma_f32_16x16x32_bf16 v[34:37], v[182:185], v[202:205], v[34:37]
	v_mfma_f32_16x16x32_bf16 v[22:25], v[168:171], v[210:213], v[22:25]
	v_mfma_f32_16x16x32_bf16 v[18:21], v[182:185], v[210:213], v[18:21]
	v_mfma_f32_16x16x32_bf16 v[6:9], v[168:171], v[218:221], v[6:9]
	v_mfma_f32_16x16x32_bf16 v[2:5], v[182:185], v[218:221], v[2:5]
	v_mfma_f32_16x16x32_bf16 v[54:57], v[172:175], v[194:197], v[54:57]
	v_mfma_f32_16x16x32_bf16 v[50:53], v[186:189], v[194:197], v[50:53]
	v_mfma_f32_16x16x32_bf16 v[38:41], v[172:175], v[206:209], v[38:41]
	v_mfma_f32_16x16x32_bf16 v[34:37], v[186:189], v[206:209], v[34:37]
	v_mfma_f32_16x16x32_bf16 v[22:25], v[172:175], v[214:217], v[22:25]
	v_mfma_f32_16x16x32_bf16 v[18:21], v[186:189], v[214:217], v[18:21]
	v_mfma_f32_16x16x32_bf16 v[6:9], v[172:175], v[222:225], v[6:9]
	v_mfma_f32_16x16x32_bf16 v[2:5], v[186:189], v[222:225], v[2:5]
.Lp1skip_3:
	s_setprio 0
	s_barrier
	s_add_u32 s0, s0, 0x100
	s_addc_u32 s1, s1, 0
	s_add_u32 s61, s61, 0x100
	s_addc_u32 s72, s72, 0
	s_cmp_ge_i32 s73, s84
	s_mov_b32 s6, s73
	s_cbranch_scc0 .LBB0_216

; __global__ void __launch_bounds__(NTHREADS, 2) fwd_megakernel(Params p) {
	.amdhsa_kernel _Z14fwd_megakernel6Params
		.amdhsa_group_segment_fixed_size 0
		.amdhsa_private_segment_fixed_size 0
		.amdhsa_kernarg_size 424
		.amdhsa_user_sgpr_count 2
		.amdhsa_user_sgpr_dispatch_ptr 0
		.amdhsa_user_sgpr_queue_ptr 0
		.amdhsa_user_sgpr_kernarg_segment_ptr 1
		.amdhsa_user_sgpr_dispatch_id 0
		.amdhsa_user_sgpr_kernarg_preload_length 0
		.amdhsa_user_sgpr_kernarg_preload_offset 0
		.amdhsa_user_sgpr_private_segment_size 0
		.amdhsa_uses_dynamic_stack 0
		.amdhsa_enable_private_segment 0
		.amdhsa_system_sgpr_workgroup_id_x 1
		.amdhsa_system_sgpr_workgroup_id_y 0
		.amdhsa_system_sgpr_workgroup_id_z 0
		.amdhsa_system_sgpr_workgroup_info 0
		.amdhsa_system_vgpr_workitem_id 2
		.amdhsa_next_free_vgpr 254
		.amdhsa_next_free_sgpr 102
		.amdhsa_accum_offset 256
		.amdhsa_reserve_vcc 1
		.amdhsa_float_round_mode_32 0
		.amdhsa_float_round_mode_16_64 0
		.amdhsa_float_denorm_mode_32 3
		.amdhsa_float_denorm_mode_16_64 3
		.amdhsa_dx10_clamp 1
		.amdhsa_ieee_mode 1
		.amdhsa_fp16_overflow 0
		.amdhsa_tg_split 0
		.amdhsa_exception_fp_ieee_invalid_op 0
		.amdhsa_exception_fp_denorm_src 0
		.amdhsa_exception_fp_ieee_div_zero 0
		.amdhsa_exception_fp_ieee_overflow 0
		.amdhsa_exception_fp_ieee_underflow 0
		.amdhsa_exception_fp_ieee_inexact 0
		.amdhsa_exception_int_div_zero 0
	.end_amdhsa_kernel

; __global__ void __launch_bounds__(NTHREADS, 2) fwd_megakernel(Params p) {
.Lfunc_end0:
	.size	_Z14fwd_megakernel6Params, .Lfunc_end0-_Z14fwd_megakernel6Params
	.set _Z14fwd_megakernel6Params.num_vgpr, 254
	.set _Z14fwd_megakernel6Params.num_agpr, 0
	.set _Z14fwd_megakernel6Params.numbered_sgpr, 102
	.set _Z14fwd_megakernel6Params.num_named_barrier, 0
	.set _Z14fwd_megakernel6Params.private_seg_size, 0
	.set _Z14fwd_megakernel6Params.uses_vcc, 1
	.set _Z14fwd_megakernel6Params.uses_flat_scratch, 0
	.set _Z14fwd_megakernel6Params.has_dyn_sized_stack, 0
	.set _Z14fwd_megakernel6Params.has_recursion, 0
	.set _Z14fwd_megakernel6Params.has_indirect_call, 0

; __global__ void __launch_bounds__(NTHREADS, 2) fwd_megakernel(Params p) {
amdhsa.kernels:
  - .agpr_count:     0
    .args:
      - .offset:         0
        .size:           168
        .value_kind:     by_value
      - .offset:         168
        .size:           4
        .value_kind:     hidden_block_count_x
      - .offset:         172
        .size:           4
        .value_kind:     hidden_block_count_y
      - .offset:         176
        .size:           4
        .value_kind:     hidden_block_count_z
      - .offset:         180
        .size:           2
        .value_kind:     hidden_group_size_x
      - .offset:         182
        .size:           2
        .value_kind:     hidden_group_size_y
      - .offset:         184
        .size:           2
        .value_kind:     hidden_group_size_z
      - .offset:         186
        .size:           2
        .value_kind:     hidden_remainder_x
      - .offset:         188
        .size:           2
        .value_kind:     hidden_remainder_y
      - .offset:         190
        .size:           2
        .value_kind:     hidden_remainder_z
      - .offset:         208
        .size:           8
        .value_kind:     hidden_global_offset_x
      - .offset:         216
        .size:           8
        .value_kind:     hidden_global_offset_y
      - .offset:         224
        .size:           8
        .value_kind:     hidden_global_offset_z
      - .offset:         232
        .size:           2
        .value_kind:     hidden_grid_dims
      - .offset:         256
        .size:           8
        .value_kind:     hidden_multigrid_sync_arg
      - .offset:         288
        .size:           4
        .value_kind:     hidden_dynamic_lds_size
    .group_segment_fixed_size: 0
    .kernarg_segment_align: 8
    .kernarg_segment_size: 424
    .language:       OpenCL C
    .language_version:
      - 2
      - 0
    .max_flat_workgroup_size: 512
    .name:           _Z14fwd_megakernel6Params
    .private_segment_fixed_size: 0
    .sgpr_count:     108
    .sgpr_spill_count: 8
    .symbol:         _Z14fwd_megakernel6Params.kd
    .uniform_work_group_size: 1
    .uses_dynamic_stack: false
    .vgpr_count:     254
    .vgpr_spill_count: 0
    .wavefront_size: 64
